# carry-scan phase: non-temporal hint on the read-once u loads (they are dead after the scan) so they do not evict proj / s_prev needed by mixer (c)
# speedup vs baseline: 1.0301x; 1.0037x over previous
; __device__ __forceinline__ int otid() { int t = threadIdx.x; asm volatile("" : "+v"(t)); return t; }
; __device__ __forceinline__ int obid() { int t = blockIdx.x; asm volatile("" : "+s"(t)); return t; }
; __device__ void phase_scan(const Params& p) {
;     unsigned char* ws = p.ws; const int tid = otid();
;     if (tid < 256) {
;         const bf16_t* __restrict__ uT = (const bf16_t*)(ws + WS_M); bf16_t* __restrict__ spT = (bf16_t*)(ws + WS_M + (size_t)S * D * 2); const float* __restrict__ dec = (const float*)(ws + WS_DEC);
;         for (int gid = obid() * 256 + tid; gid < 65536; gid += gridDim.x * 256) {
;             const int dir = gid >> 15, rem = gid & 32767, h = rem >> 13, vd = rem & 8191, d = vd & 63;
;             float s = 0.f;
;             const long step = dir ? -1 : 1; const int nfirst = dir ? NCH - 1 : 0;
;             const bf16_t* up = uT + ((size_t)(dir * NCH + nfirst) * 4 + h) * 8192 + vd; bf16_t* sp = spT + ((size_t)(dir * NCH + nfirst) * 4 + h) * 8192 + vd;
;             const float* dp = dec + ((size_t)(dir * NCH + nfirst) * 4 + h) * 64 + d;
; #pragma unroll 1
;             for (int st = 0; st < NCH; st += 64) {
;                 bf16_t ub[64]; float db[64];
; #pragma unroll
;                 for (int i = 0; i < 64; ++i) { ub[i] = up[(long)(st + i) * step * 32768]; db[i] = dp[(long)(st + i) * step * 256]; }
.LBB0_172:
	s_and_b64 vcc, exec, s[0:1]
	s_cbranch_vccz .LBB0_346
	s_cmp_gt_i32 s49, 1
	s_mov_b64 s[0:1], -1
	s_cbranch_scc0 .LBB0_349
	s_cmp_gt_i32 s49, 2
	s_cbranch_scc0 .LBB0_189
	v_writelane_b32 v184, s16, 0
	v_writelane_b32 v184, s17, 1
	v_writelane_b32 v184, s18, 2
	v_writelane_b32 v184, s19, 3
	v_writelane_b32 v184, s20, 4
	v_writelane_b32 v184, s21, 5
	v_writelane_b32 v184, s22, 6
	v_writelane_b32 v184, s23, 7
	v_writelane_b32 v184, s24, 8
	v_writelane_b32 v184, s25, 9
	v_writelane_b32 v184, s26, 10
	v_writelane_b32 v184, s27, 11
	v_writelane_b32 v184, s28, 12
	v_writelane_b32 v184, s29, 13
	v_writelane_b32 v184, s30, 14
	v_writelane_b32 v184, s31, 15
	v_readfirstlane_b32 s4, v245
	v_readlane_b32 s5, v254, 59
	v_readlane_b32 s6, v255, 0
	v_readlane_b32 s7, v255, 1
	s_lshr_b32 s4, s4, 6
	s_lshr_b32 s8, s5, 7
	s_bfe_u32 s9, s5, 0x20005
	v_and_b32_e32 v0, 63, v245
	v_lshrrev_b32_e32 v1, 4, v0
	s_mul_i32 s10, s8, 3
	v_and_b32_e32 v2, 15, v0
	v_xor_b32_e32 v1, s10, v1
	v_lshlrev_b32_e32 v1, 10, v1
	v_lshl_add_u32 v172, v2, 4, v1
	s_lshl_b32 s11, s4, 5
	s_sub_u32 s12, 0xfc, s11
	s_cmp_eq_u32 s8, 0
	s_cselect_b32 s11, s11, s12
	s_lshl_b32 s12, s8, 8
	s_add_u32 s11, s11, s12
	s_lshl_b32 s11, s11, 10
	s_lshl_b32 s12, s9, 8
	s_add_u32 s11, s11, s12
	s_add_u32 s11, s11, 0xd358000
	s_add_u32 s16, s6, s11
	s_addc_u32 s17, s7, 0
	s_cmp_eq_u32 s8, 0
	s_mov_b32 s18, 0xfffff000
	s_cselect_b32 s18, 0x1000, s18
	s_cselect_b32 s19, 0, -1
	s_lshl_b32 s10, s4, 13
	s_add_u32 s10, s10, 0x10000
	s_mov_b32 m0, s10
	s_nop 0
	global_load_lds_dwordx4 v172, s[16:17]
	s_add_u32 s16, s16, s18
	s_addc_u32 s17, s17, s19
	s_add_u32 m0, s10, 0x400
	s_nop 0
	global_load_lds_dwordx4 v172, s[16:17]
	s_add_u32 s16, s16, s18
	s_addc_u32 s17, s17, s19
	s_add_u32 m0, s10, 0x800
	s_nop 0
	global_load_lds_dwordx4 v172, s[16:17]
	s_add_u32 s16, s16, s18
	s_addc_u32 s17, s17, s19
	s_add_u32 m0, s10, 0xc00
	s_nop 0
	global_load_lds_dwordx4 v172, s[16:17]
	s_add_u32 s16, s16, s18
	s_addc_u32 s17, s17, s19
	s_add_u32 m0, s10, 0x1000
	s_nop 0
	global_load_lds_dwordx4 v172, s[16:17]
	s_add_u32 s16, s16, s18
	s_addc_u32 s17, s17, s19
	s_add_u32 m0, s10, 0x1400
	s_nop 0
	global_load_lds_dwordx4 v172, s[16:17]
	s_add_u32 s16, s16, s18
	s_addc_u32 s17, s17, s19
	s_add_u32 m0, s10, 0x1800
	s_nop 0
	global_load_lds_dwordx4 v172, s[16:17]
	s_add_u32 s16, s16, s18
	s_addc_u32 s17, s17, s19
	s_add_u32 m0, s10, 0x1c00
	s_nop 0
	global_load_lds_dwordx4 v172, s[16:17]
	s_lshr_b32 s14, s4, 2
	v_and_b32_e32 v1, 0xff, v245
	v_lshlrev_b32_e32 v7, 2, v1
	v_add_u32_e32 v7, 0x20000, v7
	v_lshlrev_b32_e32 v1, 1, v1
	v_lshlrev_b32_e32 v2, 2, v0
	s_lshl_b32 s10, s14, 15
	s_add_u32 s10, s10, 0x10000
	v_add_u32_e32 v2, s10, v2
	s_mul_i32 s10, s8, 0x1ff
	s_lshl_b32 s10, s10, 16
	s_lshl_b32 s11, s9, 14
	s_add_u32 s10, s10, s11
	s_and_b32 s11, s5, 31
	s_lshl_b32 s11, s11, 9
	s_add_u32 s10, s10, s11
	s_add_u32 s10, s10, 0x9058000
	s_add_u32 s16, s6, s10
	s_addc_u32 s17, s7, 0
	s_cmp_eq_u32 s8, 0
	s_mov_b32 s20, 0xffff0000
	s_cselect_b32 s20, 0x10000, s20
	s_cselect_b32 s21, 0, -1
	s_mov_b32 s10, 0xff800000
	s_cselect_b32 s10, 0x800000, s10
	s_cselect_b32 s11, 0, -1
	s_cmp_eq_u32 s14, 0
	s_cselect_b32 s10, 0, s10
	s_cselect_b32 s11, 0, s11
	s_add_u32 s16, s16, s10
	s_addc_u32 s17, s17, s11
	s_add_u32 s18, s16, 0x2000000
	s_addc_u32 s19, s17, 0
	v_mov_b32_e32 v3, 0
	s_cmp_eq_u32 s14, 0
	s_cbranch_scc0 .Lscan_half1
	global_load_ushort v8, v1, s[16:17] nt
	s_add_u32 s16, s16, s20
	s_addc_u32 s17, s17, s21
	global_load_ushort v9, v1, s[16:17] nt
	s_add_u32 s16, s16, s20
	s_addc_u32 s17, s17, s21
	global_load_ushort v10, v1, s[16:17] nt
	s_add_u32 s16, s16, s20
	s_addc_u32 s17, s17, s21
	global_load_ushort v11, v1, s[16:17] nt
	s_add_u32 s16, s16, s20
	s_addc_u32 s17, s17, s21
	global_load_ushort v12, v1, s[16:17] nt
	s_add_u32 s16, s16, s20
	s_addc_u32 s17, s17, s21
	global_load_ushort v13, v1, s[16:17] nt
	s_add_u32 s16, s16, s20
	s_addc_u32 s17, s17, s21
	global_load_ushort v14, v1, s[16:17] nt
	s_add_u32 s16, s16, s20
	s_addc_u32 s17, s17, s21
	global_load_ushort v15, v1, s[16:17] nt
	s_add_u32 s16, s16, s20
	s_addc_u32 s17, s17, s21
	global_load_ushort v16, v1, s[16:17] nt
	s_add_u32 s16, s16, s20
	s_addc_u32 s17, s17, s21
	global_load_ushort v17, v1, s[16:17] nt
	s_add_u32 s16, s16, s20
	s_addc_u32 s17, s17, s21
	global_load_ushort v18, v1, s[16:17] nt
	s_add_u32 s16, s16, s20
	s_addc_u32 s17, s17, s21
	global_load_ushort v19, v1, s[16:17] nt
	s_add_u32 s16, s16, s20
	s_addc_u32 s17, s17, s21
	global_load_ushort v20, v1, s[16:17] nt
	s_add_u32 s16, s16, s20
	s_addc_u32 s17, s17, s21
	global_load_ushort v21, v1, s[16:17] nt
	s_add_u32 s16, s16, s20
	s_addc_u32 s17, s17, s21
	global_load_ushort v22, v1, s[16:17] nt
	s_add_u32 s16, s16, s20
	s_addc_u32 s17, s17, s21
	global_load_ushort v23, v1, s[16:17] nt
	s_add_u32 s16, s16, s20
	s_addc_u32 s17, s17, s21
	global_load_ushort v24, v1, s[16:17] nt
	s_add_u32 s16, s16, s20
	s_addc_u32 s17, s17, s21
	global_load_ushort v25, v1, s[16:17] nt
	s_add_u32 s16, s16, s20
	s_addc_u32 s17, s17, s21
	global_load_ushort v26, v1, s[16:17] nt
	s_add_u32 s16, s16, s20
	s_addc_u32 s17, s17, s21
	global_load_ushort v27, v1, s[16:17] nt
	s_add_u32 s16, s16, s20
	s_addc_u32 s17, s17, s21
	global_load_ushort v28, v1, s[16:17] nt
	s_add_u32 s16, s16, s20
	s_addc_u32 s17, s17, s21
	global_load_ushort v29, v1, s[16:17] nt
	s_add_u32 s16, s16, s20
	s_addc_u32 s17, s17, s21
	global_load_ushort v30, v1, s[16:17] nt
	s_add_u32 s16, s16, s20
	s_addc_u32 s17, s17, s21
	global_load_ushort v31, v1, s[16:17] nt
	s_add_u32 s16, s16, s20
	s_addc_u32 s17, s17, s21
	global_load_ushort v32, v1, s[16:17] nt
; __device__ void phase_scan(const Params& p) {
;     ...
;             for (int st = 0; st < NCH; st += 64) {
;                 bf16_t ub[64]; float db[64];
; #pragma unroll
;                 for (int i = 0; i < 64; ++i) { ub[i] = up[(long)(st + i) * step * 32768]; db[i] = dp[(long)(st + i) * step * 256]; }
	s_add_u32 s16, s16, s20
	s_addc_u32 s17, s17, s21
	global_load_ushort v33, v1, s[16:17] nt
	s_add_u32 s16, s16, s20
	s_addc_u32 s17, s17, s21
	global_load_ushort v34, v1, s[16:17] nt
	s_add_u32 s16, s16, s20
	s_addc_u32 s17, s17, s21
	global_load_ushort v35, v1, s[16:17] nt
	s_add_u32 s16, s16, s20
	s_addc_u32 s17, s17, s21
	global_load_ushort v36, v1, s[16:17] nt
	s_add_u32 s16, s16, s20
	s_addc_u32 s17, s17, s21
	global_load_ushort v37, v1, s[16:17] nt
	s_add_u32 s16, s16, s20
	s_addc_u32 s17, s17, s21
	global_load_ushort v38, v1, s[16:17] nt
	s_add_u32 s16, s16, s20
	s_addc_u32 s17, s17, s21
	global_load_ushort v39, v1, s[16:17] nt
	s_add_u32 s16, s16, s20
	s_addc_u32 s17, s17, s21
	global_load_ushort v40, v1, s[16:17] nt
	s_add_u32 s16, s16, s20
	s_addc_u32 s17, s17, s21
	global_load_ushort v41, v1, s[16:17] nt
	s_add_u32 s16, s16, s20
	s_addc_u32 s17, s17, s21
	global_load_ushort v42, v1, s[16:17] nt
	s_add_u32 s16, s16, s20
	s_addc_u32 s17, s17, s21
	global_load_ushort v43, v1, s[16:17] nt
	s_add_u32 s16, s16, s20
	s_addc_u32 s17, s17, s21
	global_load_ushort v44, v1, s[16:17] nt
	s_add_u32 s16, s16, s20
	s_addc_u32 s17, s17, s21
	global_load_ushort v45, v1, s[16:17] nt
	s_add_u32 s16, s16, s20
	s_addc_u32 s17, s17, s21
	global_load_ushort v46, v1, s[16:17] nt
	s_add_u32 s16, s16, s20
	s_addc_u32 s17, s17, s21
	global_load_ushort v47, v1, s[16:17] nt
	s_add_u32 s16, s16, s20
	s_addc_u32 s17, s17, s21
	global_load_ushort v48, v1, s[16:17] nt
	s_add_u32 s16, s16, s20
	s_addc_u32 s17, s17, s21
	global_load_ushort v49, v1, s[16:17] nt
	s_add_u32 s16, s16, s20
	s_addc_u32 s17, s17, s21
	global_load_ushort v50, v1, s[16:17] nt
	s_add_u32 s16, s16, s20
	s_addc_u32 s17, s17, s21
	global_load_ushort v51, v1, s[16:17] nt
	s_add_u32 s16, s16, s20
	s_addc_u32 s17, s17, s21
	global_load_ushort v52, v1, s[16:17] nt
	s_add_u32 s16, s16, s20
	s_addc_u32 s17, s17, s21
	global_load_ushort v53, v1, s[16:17] nt
	s_add_u32 s16, s16, s20
	s_addc_u32 s17, s17, s21
	global_load_ushort v54, v1, s[16:17] nt
	s_add_u32 s16, s16, s20
	s_addc_u32 s17, s17, s21
	global_load_ushort v55, v1, s[16:17] nt
	s_add_u32 s16, s16, s20
	s_addc_u32 s17, s17, s21
	global_load_ushort v56, v1, s[16:17] nt
	s_add_u32 s16, s16, s20
	s_addc_u32 s17, s17, s21
	global_load_ushort v57, v1, s[16:17] nt
	s_add_u32 s16, s16, s20
	s_addc_u32 s17, s17, s21
	global_load_ushort v58, v1, s[16:17] nt
	s_add_u32 s16, s16, s20
	s_addc_u32 s17, s17, s21
	global_load_ushort v59, v1, s[16:17] nt
	s_add_u32 s16, s16, s20
	s_addc_u32 s17, s17, s21
	global_load_ushort v60, v1, s[16:17] nt
	s_add_u32 s16, s16, s20
	s_addc_u32 s17, s17, s21
	global_load_ushort v61, v1, s[16:17] nt
	s_add_u32 s16, s16, s20
	s_addc_u32 s17, s17, s21
	global_load_ushort v62, v1, s[16:17] nt
	s_add_u32 s16, s16, s20
	s_addc_u32 s17, s17, s21
	global_load_ushort v63, v1, s[16:17] nt
	s_add_u32 s16, s16, s20
	s_addc_u32 s17, s17, s21
	global_load_ushort v64, v1, s[16:17] nt
	s_add_u32 s16, s16, s20
	s_addc_u32 s17, s17, s21
	global_load_ushort v65, v1, s[16:17] nt
	s_add_u32 s16, s16, s20
	s_addc_u32 s17, s17, s21
	global_load_ushort v66, v1, s[16:17] nt
	s_add_u32 s16, s16, s20
	s_addc_u32 s17, s17, s21
	global_load_ushort v67, v1, s[16:17] nt
	s_add_u32 s16, s16, s20
	s_addc_u32 s17, s17, s21
	global_load_ushort v68, v1, s[16:17] nt
	s_add_u32 s16, s16, s20
	s_addc_u32 s17, s17, s21
	global_load_ushort v69, v1, s[16:17] nt
	s_add_u32 s16, s16, s20
	s_addc_u32 s17, s17, s21
	global_load_ushort v70, v1, s[16:17] nt
	s_add_u32 s16, s16, s20
	s_addc_u32 s17, s17, s21
	global_load_ushort v71, v1, s[16:17] nt
	s_add_u32 s16, s16, s20
	s_addc_u32 s17, s17, s21
	global_load_ushort v72, v1, s[16:17] nt
	s_add_u32 s16, s16, s20
	s_addc_u32 s17, s17, s21
	global_load_ushort v73, v1, s[16:17] nt
	s_add_u32 s16, s16, s20
	s_addc_u32 s17, s17, s21
	global_load_ushort v74, v1, s[16:17] nt
	s_add_u32 s16, s16, s20
	s_addc_u32 s17, s17, s21
	global_load_ushort v75, v1, s[16:17] nt
	s_add_u32 s16, s16, s20
	s_addc_u32 s17, s17, s21
	global_load_ushort v76, v1, s[16:17] nt
	s_add_u32 s16, s16, s20
	s_addc_u32 s17, s17, s21
	global_load_ushort v77, v1, s[16:17] nt
	s_add_u32 s16, s16, s20
	s_addc_u32 s17, s17, s21
	global_load_ushort v78, v1, s[16:17] nt
	s_add_u32 s16, s16, s20
	s_addc_u32 s17, s17, s21
	global_load_ushort v79, v1, s[16:17] nt
	s_add_u32 s16, s16, s20
	s_addc_u32 s17, s17, s21
	global_load_ushort v80, v1, s[16:17] nt
	s_add_u32 s16, s16, s20
	s_addc_u32 s17, s17, s21
	global_load_ushort v81, v1, s[16:17] nt
	s_add_u32 s16, s16, s20
	s_addc_u32 s17, s17, s21
	global_load_ushort v82, v1, s[16:17] nt
	s_add_u32 s16, s16, s20
	s_addc_u32 s17, s17, s21
	global_load_ushort v83, v1, s[16:17] nt
	s_add_u32 s16, s16, s20
	s_addc_u32 s17, s17, s21
	global_load_ushort v84, v1, s[16:17] nt
	s_add_u32 s16, s16, s20
	s_addc_u32 s17, s17, s21
	global_load_ushort v85, v1, s[16:17] nt
	s_add_u32 s16, s16, s20
	s_addc_u32 s17, s17, s21
	global_load_ushort v86, v1, s[16:17] nt
	s_add_u32 s16, s16, s20
	s_addc_u32 s17, s17, s21
	global_load_ushort v87, v1, s[16:17] nt
	s_add_u32 s16, s16, s20
	s_addc_u32 s17, s17, s21
	global_load_ushort v88, v1, s[16:17] nt
	s_add_u32 s16, s16, s20
	s_addc_u32 s17, s17, s21
	global_load_ushort v89, v1, s[16:17] nt
	s_add_u32 s16, s16, s20
	s_addc_u32 s17, s17, s21
	global_load_ushort v90, v1, s[16:17] nt
	s_add_u32 s16, s16, s20
	s_addc_u32 s17, s17, s21
	global_load_ushort v91, v1, s[16:17] nt
	s_add_u32 s16, s16, s20
	s_addc_u32 s17, s17, s21
	global_load_ushort v92, v1, s[16:17] nt
	s_add_u32 s16, s16, s20
	s_addc_u32 s17, s17, s21
	global_load_ushort v93, v1, s[16:17] nt
	s_add_u32 s16, s16, s20
; __device__ void phase_scan(const Params& p) {
;     ...
;             for (int st = 0; st < NCH; st += 64) {
;                 bf16_t ub[64]; float db[64];
; #pragma unroll
;                 for (int i = 0; i < 64; ++i) { ub[i] = up[(long)(st + i) * step * 32768]; db[i] = dp[(long)(st + i) * step * 256]; }
	s_addc_u32 s17, s17, s21
	global_load_ushort v94, v1, s[16:17] nt
	s_add_u32 s16, s16, s20
	s_addc_u32 s17, s17, s21
	global_load_ushort v95, v1, s[16:17] nt
	s_add_u32 s16, s16, s20
	s_addc_u32 s17, s17, s21
	global_load_ushort v96, v1, s[16:17] nt
	s_add_u32 s16, s16, s20
	s_addc_u32 s17, s17, s21
	global_load_ushort v97, v1, s[16:17] nt
	s_add_u32 s16, s16, s20
	s_addc_u32 s17, s17, s21
	global_load_ushort v98, v1, s[16:17] nt
	s_add_u32 s16, s16, s20
	s_addc_u32 s17, s17, s21
	global_load_ushort v99, v1, s[16:17] nt
	s_add_u32 s16, s16, s20
	s_addc_u32 s17, s17, s21
	global_load_ushort v100, v1, s[16:17] nt
	s_add_u32 s16, s16, s20
	s_addc_u32 s17, s17, s21
	global_load_ushort v101, v1, s[16:17] nt
	s_add_u32 s16, s16, s20
	s_addc_u32 s17, s17, s21
	global_load_ushort v102, v1, s[16:17] nt
	s_add_u32 s16, s16, s20
	s_addc_u32 s17, s17, s21
	global_load_ushort v103, v1, s[16:17] nt
	s_add_u32 s16, s16, s20
	s_addc_u32 s17, s17, s21
	global_load_ushort v104, v1, s[16:17] nt
	s_add_u32 s16, s16, s20
	s_addc_u32 s17, s17, s21
	global_load_ushort v105, v1, s[16:17] nt
	s_add_u32 s16, s16, s20
	s_addc_u32 s17, s17, s21
	global_load_ushort v106, v1, s[16:17] nt
	s_add_u32 s16, s16, s20
	s_addc_u32 s17, s17, s21
	global_load_ushort v107, v1, s[16:17] nt
	s_add_u32 s16, s16, s20
	s_addc_u32 s17, s17, s21
	global_load_ushort v108, v1, s[16:17] nt
	s_add_u32 s16, s16, s20
	s_addc_u32 s17, s17, s21
	global_load_ushort v109, v1, s[16:17] nt
	s_add_u32 s16, s16, s20
	s_addc_u32 s17, s17, s21
	global_load_ushort v110, v1, s[16:17] nt
	s_add_u32 s16, s16, s20
	s_addc_u32 s17, s17, s21
	global_load_ushort v111, v1, s[16:17] nt
	s_add_u32 s16, s16, s20
	s_addc_u32 s17, s17, s21
	global_load_ushort v112, v1, s[16:17] nt
	s_add_u32 s16, s16, s20
	s_addc_u32 s17, s17, s21
	global_load_ushort v113, v1, s[16:17] nt
	s_add_u32 s16, s16, s20
	s_addc_u32 s17, s17, s21
	global_load_ushort v114, v1, s[16:17] nt
	s_add_u32 s16, s16, s20
	s_addc_u32 s17, s17, s21
	global_load_ushort v115, v1, s[16:17] nt
	s_add_u32 s16, s16, s20
	s_addc_u32 s17, s17, s21
	global_load_ushort v116, v1, s[16:17] nt
	s_add_u32 s16, s16, s20
	s_addc_u32 s17, s17, s21
	global_load_ushort v117, v1, s[16:17] nt
	s_add_u32 s16, s16, s20
	s_addc_u32 s17, s17, s21
	global_load_ushort v118, v1, s[16:17] nt
	s_add_u32 s16, s16, s20
	s_addc_u32 s17, s17, s21
	global_load_ushort v119, v1, s[16:17] nt
	s_add_u32 s16, s16, s20
	s_addc_u32 s17, s17, s21
	global_load_ushort v120, v1, s[16:17] nt
	s_add_u32 s16, s16, s20
	s_addc_u32 s17, s17, s21
	global_load_ushort v121, v1, s[16:17] nt
	s_add_u32 s16, s16, s20
	s_addc_u32 s17, s17, s21
	global_load_ushort v122, v1, s[16:17] nt
	s_add_u32 s16, s16, s20
	s_addc_u32 s17, s17, s21
	global_load_ushort v123, v1, s[16:17] nt
	s_add_u32 s16, s16, s20
	s_addc_u32 s17, s17, s21
	global_load_ushort v124, v1, s[16:17] nt
	s_add_u32 s16, s16, s20
	s_addc_u32 s17, s17, s21
	global_load_ushort v125, v1, s[16:17] nt
	s_add_u32 s16, s16, s20
	s_addc_u32 s17, s17, s21
	global_load_ushort v126, v1, s[16:17] nt
	s_add_u32 s16, s16, s20
	s_addc_u32 s17, s17, s21
	global_load_ushort v127, v1, s[16:17] nt
	s_add_u32 s16, s16, s20
	s_addc_u32 s17, s17, s21
	global_load_ushort v128, v1, s[16:17] nt
	s_add_u32 s16, s16, s20
	s_addc_u32 s17, s17, s21
	global_load_ushort v129, v1, s[16:17] nt
	s_add_u32 s16, s16, s20
	s_addc_u32 s17, s17, s21
	global_load_ushort v130, v1, s[16:17] nt
	s_add_u32 s16, s16, s20
	s_addc_u32 s17, s17, s21
	global_load_ushort v131, v1, s[16:17] nt
	s_add_u32 s16, s16, s20
	s_addc_u32 s17, s17, s21
	global_load_ushort v132, v1, s[16:17] nt
	s_add_u32 s16, s16, s20
	s_addc_u32 s17, s17, s21
	global_load_ushort v133, v1, s[16:17] nt
	s_add_u32 s16, s16, s20
	s_addc_u32 s17, s17, s21
	global_load_ushort v134, v1, s[16:17] nt
	s_add_u32 s16, s16, s20
	s_addc_u32 s17, s17, s21
	global_load_ushort v135, v1, s[16:17] nt
	s_waitcnt vmcnt(63)
	s_barrier
	s_branch .Lscan_steps
.Lscan_half1:
	s_cmp_lt_u32 s5, 32
	s_cbranch_scc1 .Lscan_lru
	global_load_ushort v8, v1, s[16:17] nt
	s_add_u32 s16, s16, s20
	s_addc_u32 s17, s17, s21
	global_load_ushort v9, v1, s[16:17] nt
	s_add_u32 s16, s16, s20
	s_addc_u32 s17, s17, s21
	global_load_ushort v10, v1, s[16:17] nt
	s_add_u32 s16, s16, s20
	s_addc_u32 s17, s17, s21
	global_load_ushort v11, v1, s[16:17] nt
	s_add_u32 s16, s16, s20
	s_addc_u32 s17, s17, s21
	global_load_ushort v12, v1, s[16:17] nt
	s_add_u32 s16, s16, s20
	s_addc_u32 s17, s17, s21
	global_load_ushort v13, v1, s[16:17] nt
	s_add_u32 s16, s16, s20
	s_addc_u32 s17, s17, s21
	global_load_ushort v14, v1, s[16:17] nt
	s_add_u32 s16, s16, s20
	s_addc_u32 s17, s17, s21
	global_load_ushort v15, v1, s[16:17] nt
	s_add_u32 s16, s16, s20
	s_addc_u32 s17, s17, s21
	global_load_ushort v16, v1, s[16:17] nt
	s_add_u32 s16, s16, s20
	s_addc_u32 s17, s17, s21
	global_load_ushort v17, v1, s[16:17] nt
	s_add_u32 s16, s16, s20
	s_addc_u32 s17, s17, s21
	global_load_ushort v18, v1, s[16:17] nt
	s_add_u32 s16, s16, s20
	s_addc_u32 s17, s17, s21
	global_load_ushort v19, v1, s[16:17] nt
	s_add_u32 s16, s16, s20
	s_addc_u32 s17, s17, s21
	global_load_ushort v20, v1, s[16:17] nt
	s_add_u32 s16, s16, s20
	s_addc_u32 s17, s17, s21
	global_load_ushort v21, v1, s[16:17] nt
	s_add_u32 s16, s16, s20
	s_addc_u32 s17, s17, s21
	global_load_ushort v22, v1, s[16:17] nt
	s_add_u32 s16, s16, s20
	s_addc_u32 s17, s17, s21
	global_load_ushort v23, v1, s[16:17] nt
	s_add_u32 s16, s16, s20
	s_addc_u32 s17, s17, s21
	global_load_ushort v24, v1, s[16:17] nt
	s_add_u32 s16, s16, s20
	s_addc_u32 s17, s17, s21
	global_load_ushort v25, v1, s[16:17] nt
	s_add_u32 s16, s16, s20
	s_addc_u32 s17, s17, s21
; __device__ void phase_scan(const Params& p) {
;     ...
;             for (int st = 0; st < NCH; st += 64) {
;                 bf16_t ub[64]; float db[64];
; #pragma unroll
;                 for (int i = 0; i < 64; ++i) { ub[i] = up[(long)(st + i) * step * 32768]; db[i] = dp[(long)(st + i) * step * 256]; }
	global_load_ushort v26, v1, s[16:17] nt
	s_add_u32 s16, s16, s20
	s_addc_u32 s17, s17, s21
	global_load_ushort v27, v1, s[16:17] nt
	s_add_u32 s16, s16, s20
	s_addc_u32 s17, s17, s21
	global_load_ushort v28, v1, s[16:17] nt
	s_add_u32 s16, s16, s20
	s_addc_u32 s17, s17, s21
	global_load_ushort v29, v1, s[16:17] nt
	s_add_u32 s16, s16, s20
	s_addc_u32 s17, s17, s21
	global_load_ushort v30, v1, s[16:17] nt
	s_add_u32 s16, s16, s20
	s_addc_u32 s17, s17, s21
	global_load_ushort v31, v1, s[16:17] nt
	s_add_u32 s16, s16, s20
	s_addc_u32 s17, s17, s21
	global_load_ushort v32, v1, s[16:17] nt
	s_add_u32 s16, s16, s20
	s_addc_u32 s17, s17, s21
	global_load_ushort v33, v1, s[16:17] nt
	s_add_u32 s16, s16, s20
	s_addc_u32 s17, s17, s21
	global_load_ushort v34, v1, s[16:17] nt
	s_add_u32 s16, s16, s20
	s_addc_u32 s17, s17, s21
	global_load_ushort v35, v1, s[16:17] nt
	s_add_u32 s16, s16, s20
	s_addc_u32 s17, s17, s21
	global_load_ushort v36, v1, s[16:17] nt
	s_add_u32 s16, s16, s20
	s_addc_u32 s17, s17, s21
	global_load_ushort v37, v1, s[16:17] nt
	s_add_u32 s16, s16, s20
	s_addc_u32 s17, s17, s21
	global_load_ushort v38, v1, s[16:17] nt
	s_add_u32 s16, s16, s20
	s_addc_u32 s17, s17, s21
	global_load_ushort v39, v1, s[16:17] nt
	s_add_u32 s16, s16, s20
	s_addc_u32 s17, s17, s21
	global_load_ushort v40, v1, s[16:17] nt
	s_add_u32 s16, s16, s20
	s_addc_u32 s17, s17, s21
	global_load_ushort v41, v1, s[16:17] nt
	s_add_u32 s16, s16, s20
	s_addc_u32 s17, s17, s21
	global_load_ushort v42, v1, s[16:17] nt
	s_add_u32 s16, s16, s20
	s_addc_u32 s17, s17, s21
	global_load_ushort v43, v1, s[16:17] nt
	s_add_u32 s16, s16, s20
	s_addc_u32 s17, s17, s21
	global_load_ushort v44, v1, s[16:17] nt
	s_add_u32 s16, s16, s20
	s_addc_u32 s17, s17, s21
	global_load_ushort v45, v1, s[16:17] nt
	s_add_u32 s16, s16, s20
	s_addc_u32 s17, s17, s21
	global_load_ushort v46, v1, s[16:17] nt
	s_add_u32 s16, s16, s20
	s_addc_u32 s17, s17, s21
	global_load_ushort v47, v1, s[16:17] nt
	s_add_u32 s16, s16, s20
	s_addc_u32 s17, s17, s21
	global_load_ushort v48, v1, s[16:17] nt
	s_add_u32 s16, s16, s20
	s_addc_u32 s17, s17, s21
	global_load_ushort v49, v1, s[16:17] nt
	s_add_u32 s16, s16, s20
	s_addc_u32 s17, s17, s21
	global_load_ushort v50, v1, s[16:17] nt
	s_add_u32 s16, s16, s20
	s_addc_u32 s17, s17, s21
	global_load_ushort v51, v1, s[16:17] nt
	s_add_u32 s16, s16, s20
	s_addc_u32 s17, s17, s21
	global_load_ushort v52, v1, s[16:17] nt
	s_add_u32 s16, s16, s20
	s_addc_u32 s17, s17, s21
	global_load_ushort v53, v1, s[16:17] nt
	s_add_u32 s16, s16, s20
	s_addc_u32 s17, s17, s21
	global_load_ushort v54, v1, s[16:17] nt
	s_add_u32 s16, s16, s20
	s_addc_u32 s17, s17, s21
	global_load_ushort v55, v1, s[16:17] nt
	s_add_u32 s16, s16, s20
	s_addc_u32 s17, s17, s21
	global_load_ushort v56, v1, s[16:17] nt
	s_add_u32 s16, s16, s20
	s_addc_u32 s17, s17, s21
	global_load_ushort v57, v1, s[16:17] nt
	s_add_u32 s16, s16, s20
	s_addc_u32 s17, s17, s21
	global_load_ushort v58, v1, s[16:17] nt
	s_add_u32 s16, s16, s20
	s_addc_u32 s17, s17, s21
	global_load_ushort v59, v1, s[16:17] nt
	s_add_u32 s16, s16, s20
	s_addc_u32 s17, s17, s21
	global_load_ushort v60, v1, s[16:17] nt
	s_add_u32 s16, s16, s20
	s_addc_u32 s17, s17, s21
	global_load_ushort v61, v1, s[16:17] nt
	s_add_u32 s16, s16, s20
	s_addc_u32 s17, s17, s21
	global_load_ushort v62, v1, s[16:17] nt
	s_add_u32 s16, s16, s20
	s_addc_u32 s17, s17, s21
	global_load_ushort v63, v1, s[16:17] nt
	s_add_u32 s16, s16, s20
	s_addc_u32 s17, s17, s21
	global_load_ushort v64, v1, s[16:17] nt
	s_add_u32 s16, s16, s20
	s_addc_u32 s17, s17, s21
	global_load_ushort v65, v1, s[16:17] nt
	s_add_u32 s16, s16, s20
	s_addc_u32 s17, s17, s21
	global_load_ushort v66, v1, s[16:17] nt
	s_add_u32 s16, s16, s20
	s_addc_u32 s17, s17, s21
	global_load_ushort v67, v1, s[16:17] nt
	s_add_u32 s16, s16, s20
	s_addc_u32 s17, s17, s21
	global_load_ushort v68, v1, s[16:17] nt
	s_add_u32 s16, s16, s20
	s_addc_u32 s17, s17, s21
	global_load_ushort v69, v1, s[16:17] nt
	s_add_u32 s16, s16, s20
	s_addc_u32 s17, s17, s21
	global_load_ushort v70, v1, s[16:17] nt
	s_add_u32 s16, s16, s20
	s_addc_u32 s17, s17, s21
	global_load_ushort v71, v1, s[16:17] nt
	s_add_u32 s16, s16, s20
	s_addc_u32 s17, s17, s21
	global_load_ushort v72, v1, s[16:17] nt
	s_add_u32 s16, s16, s20
	s_addc_u32 s17, s17, s21
	global_load_ushort v73, v1, s[16:17] nt
	s_add_u32 s16, s16, s20
	s_addc_u32 s17, s17, s21
	global_load_ushort v74, v1, s[16:17] nt
	s_add_u32 s16, s16, s20
	s_addc_u32 s17, s17, s21
	global_load_ushort v75, v1, s[16:17] nt
	s_add_u32 s16, s16, s20
	s_addc_u32 s17, s17, s21
	global_load_ushort v76, v1, s[16:17] nt
	s_add_u32 s16, s16, s20
	s_addc_u32 s17, s17, s21
	global_load_ushort v77, v1, s[16:17] nt
	s_add_u32 s16, s16, s20
	s_addc_u32 s17, s17, s21
	global_load_ushort v78, v1, s[16:17] nt
	s_add_u32 s16, s16, s20
	s_addc_u32 s17, s17, s21
	global_load_ushort v79, v1, s[16:17] nt
	s_add_u32 s16, s16, s20
	s_addc_u32 s17, s17, s21
	global_load_ushort v80, v1, s[16:17] nt
	s_add_u32 s16, s16, s20
	s_addc_u32 s17, s17, s21
	global_load_ushort v81, v1, s[16:17] nt
	s_add_u32 s16, s16, s20
	s_addc_u32 s17, s17, s21
	global_load_ushort v82, v1, s[16:17] nt
	s_add_u32 s16, s16, s20
	s_addc_u32 s17, s17, s21
	global_load_ushort v83, v1, s[16:17] nt
	s_add_u32 s16, s16, s20
	s_addc_u32 s17, s17, s21
	global_load_ushort v84, v1, s[16:17] nt
	s_add_u32 s16, s16, s20
	s_addc_u32 s17, s17, s21
	global_load_ushort v85, v1, s[16:17] nt
	s_add_u32 s16, s16, s20
	s_addc_u32 s17, s17, s21
	global_load_ushort v86, v1, s[16:17] nt
	s_add_u32 s16, s16, s20
	s_addc_u32 s17, s17, s21
	global_load_ushort v87, v1, s[16:17] nt
; __device__ void phase_scan(const Params& p) {
;     ...
;             for (int st = 0; st < NCH; st += 64) {
;                 bf16_t ub[64]; float db[64];
; #pragma unroll
;                 for (int i = 0; i < 64; ++i) { ub[i] = up[(long)(st + i) * step * 32768]; db[i] = dp[(long)(st + i) * step * 256]; }
	s_add_u32 s16, s16, s20
	s_addc_u32 s17, s17, s21
	global_load_ushort v88, v1, s[16:17] nt
	s_add_u32 s16, s16, s20
	s_addc_u32 s17, s17, s21
	global_load_ushort v89, v1, s[16:17] nt
	s_add_u32 s16, s16, s20
	s_addc_u32 s17, s17, s21
	global_load_ushort v90, v1, s[16:17] nt
	s_add_u32 s16, s16, s20
	s_addc_u32 s17, s17, s21
	global_load_ushort v91, v1, s[16:17] nt
	s_add_u32 s16, s16, s20
	s_addc_u32 s17, s17, s21
	global_load_ushort v92, v1, s[16:17] nt
	s_add_u32 s16, s16, s20
	s_addc_u32 s17, s17, s21
	global_load_ushort v93, v1, s[16:17] nt
	s_add_u32 s16, s16, s20
	s_addc_u32 s17, s17, s21
	global_load_ushort v94, v1, s[16:17] nt
	s_add_u32 s16, s16, s20
	s_addc_u32 s17, s17, s21
	global_load_ushort v95, v1, s[16:17] nt
	s_add_u32 s16, s16, s20
	s_addc_u32 s17, s17, s21
	global_load_ushort v96, v1, s[16:17] nt
	s_add_u32 s16, s16, s20
	s_addc_u32 s17, s17, s21
	global_load_ushort v97, v1, s[16:17] nt
	s_add_u32 s16, s16, s20
	s_addc_u32 s17, s17, s21
	global_load_ushort v98, v1, s[16:17] nt
	s_add_u32 s16, s16, s20
	s_addc_u32 s17, s17, s21
	global_load_ushort v99, v1, s[16:17] nt
	s_add_u32 s16, s16, s20
	s_addc_u32 s17, s17, s21
	global_load_ushort v100, v1, s[16:17] nt
	s_add_u32 s16, s16, s20
	s_addc_u32 s17, s17, s21
	global_load_ushort v101, v1, s[16:17] nt
	s_add_u32 s16, s16, s20
	s_addc_u32 s17, s17, s21
	global_load_ushort v102, v1, s[16:17] nt
	s_add_u32 s16, s16, s20
	s_addc_u32 s17, s17, s21
	global_load_ushort v103, v1, s[16:17] nt
	s_add_u32 s16, s16, s20
	s_addc_u32 s17, s17, s21
	global_load_ushort v104, v1, s[16:17] nt
	s_add_u32 s16, s16, s20
	s_addc_u32 s17, s17, s21
	global_load_ushort v105, v1, s[16:17] nt
	s_add_u32 s16, s16, s20
	s_addc_u32 s17, s17, s21
	global_load_ushort v106, v1, s[16:17] nt
	s_add_u32 s16, s16, s20
	s_addc_u32 s17, s17, s21
	global_load_ushort v107, v1, s[16:17] nt
	s_add_u32 s16, s16, s20
	s_addc_u32 s17, s17, s21
	global_load_ushort v108, v1, s[16:17] nt
	s_add_u32 s16, s16, s20
	s_addc_u32 s17, s17, s21
	global_load_ushort v109, v1, s[16:17] nt
	s_add_u32 s16, s16, s20
	s_addc_u32 s17, s17, s21
	global_load_ushort v110, v1, s[16:17] nt
	s_add_u32 s16, s16, s20
	s_addc_u32 s17, s17, s21
	global_load_ushort v111, v1, s[16:17] nt
	s_add_u32 s16, s16, s20
	s_addc_u32 s17, s17, s21
	global_load_ushort v112, v1, s[16:17] nt
	s_add_u32 s16, s16, s20
	s_addc_u32 s17, s17, s21
	global_load_ushort v113, v1, s[16:17] nt
	s_add_u32 s16, s16, s20
	s_addc_u32 s17, s17, s21
	global_load_ushort v114, v1, s[16:17] nt
	s_add_u32 s16, s16, s20
	s_addc_u32 s17, s17, s21
	global_load_ushort v115, v1, s[16:17] nt
	s_add_u32 s16, s16, s20
	s_addc_u32 s17, s17, s21
	global_load_ushort v116, v1, s[16:17] nt
	s_add_u32 s16, s16, s20
	s_addc_u32 s17, s17, s21
	global_load_ushort v117, v1, s[16:17] nt
	s_add_u32 s16, s16, s20
	s_addc_u32 s17, s17, s21
	global_load_ushort v118, v1, s[16:17] nt
	s_add_u32 s16, s16, s20
	s_addc_u32 s17, s17, s21
	global_load_ushort v119, v1, s[16:17] nt
	s_add_u32 s16, s16, s20
	s_addc_u32 s17, s17, s21
	global_load_ushort v120, v1, s[16:17] nt
	s_add_u32 s16, s16, s20
	s_addc_u32 s17, s17, s21
	global_load_ushort v121, v1, s[16:17] nt
	s_add_u32 s16, s16, s20
	s_addc_u32 s17, s17, s21
	global_load_ushort v122, v1, s[16:17] nt
	s_add_u32 s16, s16, s20
	s_addc_u32 s17, s17, s21
	global_load_ushort v123, v1, s[16:17] nt
	s_add_u32 s16, s16, s20
	s_addc_u32 s17, s17, s21
	global_load_ushort v124, v1, s[16:17] nt
	s_add_u32 s16, s16, s20
	s_addc_u32 s17, s17, s21
	global_load_ushort v125, v1, s[16:17] nt
	s_add_u32 s16, s16, s20
	s_addc_u32 s17, s17, s21
	global_load_ushort v126, v1, s[16:17] nt
	s_add_u32 s16, s16, s20
	s_addc_u32 s17, s17, s21
	global_load_ushort v127, v1, s[16:17] nt
	s_add_u32 s16, s16, s20
	s_addc_u32 s17, s17, s21
	global_load_ushort v128, v1, s[16:17] nt
	s_add_u32 s16, s16, s20
	s_addc_u32 s17, s17, s21
	global_load_ushort v129, v1, s[16:17] nt
	s_add_u32 s16, s16, s20
	s_addc_u32 s17, s17, s21
	global_load_ushort v130, v1, s[16:17] nt
	s_add_u32 s16, s16, s20
	s_addc_u32 s17, s17, s21
	global_load_ushort v131, v1, s[16:17] nt
	s_add_u32 s16, s16, s20
	s_addc_u32 s17, s17, s21
	global_load_ushort v132, v1, s[16:17] nt
	s_add_u32 s16, s16, s20
	s_addc_u32 s17, s17, s21
	global_load_ushort v133, v1, s[16:17] nt
	s_add_u32 s16, s16, s20
	s_addc_u32 s17, s17, s21
	global_load_ushort v134, v1, s[16:17] nt
	s_add_u32 s16, s16, s20
	s_addc_u32 s17, s17, s21
	global_load_ushort v135, v1, s[16:17] nt
	s_waitcnt vmcnt(63)
	s_barrier
	s_branch .Lscan_second
; __device__ __forceinline__ int obid() { int t = blockIdx.x; asm volatile("" : "+s"(t)); return t; }
; __device__ void phase_scan(const Params& p) {
;     ...
;     } else if (tid < 384 && obid() < 8) {
;         const float* __restrict__ Aprod = (const float*)(ws + WS_AP); const float* __restrict__ Hend = (const float*)(ws + WS_HE); float* __restrict__ carry = (float*)(ws + WS_CA);
;         const int gid = obid() * 128 + (tid - 256); const int dir = gid >> 9, ch = gid & 511;
;         float hc = 0.f;
;         const long step = dir ? -1 : 1; const size_t base = (size_t)(dir * NCH + (dir ? NCH - 1 : 0)) * 512 + ch;
; #pragma unroll 1
;         for (int st = 0; st < NCH; st += 64) {
;             float ab[64], hb[64];
; #pragma unroll
;             for (int i = 0; i < 64; ++i) { ab[i] = Aprod[base + (long)(st + i) * step * 512]; hb[i] = Hend[base + (long)(st + i) * step * 512]; }
.Lscan_lru:
	s_waitcnt vmcnt(0)
	s_barrier
	s_lshl_b32 s10, s5, 2
	s_add_u32 s10, s10, s4
	s_sub_u32 s10, s10, 4
	s_lshr_b32 s11, s5, 4
	s_and_b32 s10, s10, 63
	s_lshl_b32 s10, s10, 5
	v_lshrrev_b32_e32 v75, 3, v0
	v_lshlrev_b32_e32 v76, 5, v75
	s_mul_i32 s12, s11, 0xff
	v_and_b32_e32 v77, 7, v0
	v_xor_b32_e32 v76, s12, v76
	v_lshlrev_b32_e32 v76, 11, v76
	v_lshl_add_u32 v74, v77, 2, v76
	v_add_u32_e32 v74, s10, v74
	s_lshl_b32 s12, s11, 19
	s_add_u32 s12, s12, 0xd058000
	s_add_u32 s24, s6, s12
	s_addc_u32 s25, s7, 0
	s_add_u32 s26, s24, 0x100000
	s_addc_u32 s27, s25, 0
	s_add_u32 s28, s24, 0x200000
	s_addc_u32 s29, s25, 0
	s_cmp_eq_u32 s11, 0
	s_mov_b32 s30, 0xfffff800
	s_cselect_b32 s30, 0x800, s30
	s_cselect_b32 s31, 0, -1
	global_load_dword v8, v74, s[24:25]
	global_load_dword v40, v74, s[26:27]
	s_add_u32 s24, s24, s30
	s_addc_u32 s25, s25, s31
	s_add_u32 s26, s26, s30
	s_addc_u32 s27, s27, s31
	global_load_dword v9, v74, s[24:25]
	global_load_dword v41, v74, s[26:27]
	s_add_u32 s24, s24, s30
	s_addc_u32 s25, s25, s31
	s_add_u32 s26, s26, s30
	s_addc_u32 s27, s27, s31
	global_load_dword v10, v74, s[24:25]
	global_load_dword v42, v74, s[26:27]
	s_add_u32 s24, s24, s30
	s_addc_u32 s25, s25, s31
	s_add_u32 s26, s26, s30
	s_addc_u32 s27, s27, s31
	global_load_dword v11, v74, s[24:25]
	global_load_dword v43, v74, s[26:27]
	s_add_u32 s24, s24, s30
	s_addc_u32 s25, s25, s31
	s_add_u32 s26, s26, s30
	s_addc_u32 s27, s27, s31
	global_load_dword v12, v74, s[24:25]
	global_load_dword v44, v74, s[26:27]
	s_add_u32 s24, s24, s30
	s_addc_u32 s25, s25, s31
	s_add_u32 s26, s26, s30
	s_addc_u32 s27, s27, s31
	global_load_dword v13, v74, s[24:25]
	global_load_dword v45, v74, s[26:27]
	s_add_u32 s24, s24, s30
	s_addc_u32 s25, s25, s31
	s_add_u32 s26, s26, s30
	s_addc_u32 s27, s27, s31
	global_load_dword v14, v74, s[24:25]
	global_load_dword v46, v74, s[26:27]
	s_add_u32 s24, s24, s30
	s_addc_u32 s25, s25, s31
	s_add_u32 s26, s26, s30
	s_addc_u32 s27, s27, s31
	global_load_dword v15, v74, s[24:25]
	global_load_dword v47, v74, s[26:27]
	s_add_u32 s24, s24, s30
	s_addc_u32 s25, s25, s31
	s_add_u32 s26, s26, s30
	s_addc_u32 s27, s27, s31
	global_load_dword v16, v74, s[24:25]
	global_load_dword v48, v74, s[26:27]
	s_add_u32 s24, s24, s30
	s_addc_u32 s25, s25, s31
	s_add_u32 s26, s26, s30
	s_addc_u32 s27, s27, s31
	global_load_dword v17, v74, s[24:25]
	global_load_dword v49, v74, s[26:27]
	s_add_u32 s24, s24, s30
	s_addc_u32 s25, s25, s31
	s_add_u32 s26, s26, s30
	s_addc_u32 s27, s27, s31
	global_load_dword v18, v74, s[24:25]
	global_load_dword v50, v74, s[26:27]
	s_add_u32 s24, s24, s30
	s_addc_u32 s25, s25, s31
	s_add_u32 s26, s26, s30
	s_addc_u32 s27, s27, s31
	global_load_dword v19, v74, s[24:25]
	global_load_dword v51, v74, s[26:27]
	s_add_u32 s24, s24, s30
	s_addc_u32 s25, s25, s31
	s_add_u32 s26, s26, s30
	s_addc_u32 s27, s27, s31
	global_load_dword v20, v74, s[24:25]
	global_load_dword v52, v74, s[26:27]
	s_add_u32 s24, s24, s30
	s_addc_u32 s25, s25, s31
	s_add_u32 s26, s26, s30
	s_addc_u32 s27, s27, s31
	global_load_dword v21, v74, s[24:25]
	global_load_dword v53, v74, s[26:27]
	s_add_u32 s24, s24, s30
	s_addc_u32 s25, s25, s31
	s_add_u32 s26, s26, s30
	s_addc_u32 s27, s27, s31
	global_load_dword v22, v74, s[24:25]
	global_load_dword v54, v74, s[26:27]
	s_add_u32 s24, s24, s30
	s_addc_u32 s25, s25, s31
	s_add_u32 s26, s26, s30
	s_addc_u32 s27, s27, s31
	global_load_dword v23, v74, s[24:25]
	global_load_dword v55, v74, s[26:27]
	s_add_u32 s24, s24, s30
	s_addc_u32 s25, s25, s31
	s_add_u32 s26, s26, s30
	s_addc_u32 s27, s27, s31
	global_load_dword v24, v74, s[24:25]
	global_load_dword v56, v74, s[26:27]
	s_add_u32 s24, s24, s30
	s_addc_u32 s25, s25, s31
	s_add_u32 s26, s26, s30
	s_addc_u32 s27, s27, s31
	global_load_dword v25, v74, s[24:25]
	global_load_dword v57, v74, s[26:27]
	s_add_u32 s24, s24, s30
	s_addc_u32 s25, s25, s31
	s_add_u32 s26, s26, s30
	s_addc_u32 s27, s27, s31
	global_load_dword v26, v74, s[24:25]
	global_load_dword v58, v74, s[26:27]
	s_add_u32 s24, s24, s30
	s_addc_u32 s25, s25, s31
	s_add_u32 s26, s26, s30
	s_addc_u32 s27, s27, s31
	global_load_dword v27, v74, s[24:25]
	global_load_dword v59, v74, s[26:27]
	s_add_u32 s24, s24, s30
	s_addc_u32 s25, s25, s31
	s_add_u32 s26, s26, s30
	s_addc_u32 s27, s27, s31
	global_load_dword v28, v74, s[24:25]
	global_load_dword v60, v74, s[26:27]
	s_add_u32 s24, s24, s30
	s_addc_u32 s25, s25, s31
	s_add_u32 s26, s26, s30
	s_addc_u32 s27, s27, s31
	global_load_dword v29, v74, s[24:25]
	global_load_dword v61, v74, s[26:27]
	s_add_u32 s24, s24, s30
	s_addc_u32 s25, s25, s31
	s_add_u32 s26, s26, s30
	s_addc_u32 s27, s27, s31
	global_load_dword v30, v74, s[24:25]
	global_load_dword v62, v74, s[26:27]
	s_add_u32 s24, s24, s30
	s_addc_u32 s25, s25, s31
	s_add_u32 s26, s26, s30
	s_addc_u32 s27, s27, s31
	global_load_dword v31, v74, s[24:25]
	global_load_dword v63, v74, s[26:27]
	s_add_u32 s24, s24, s30
	s_addc_u32 s25, s25, s31
	s_add_u32 s26, s26, s30
	s_addc_u32 s27, s27, s31
	global_load_dword v32, v74, s[24:25]
	global_load_dword v64, v74, s[26:27]
	s_add_u32 s24, s24, s30
	s_addc_u32 s25, s25, s31
	s_add_u32 s26, s26, s30
	s_addc_u32 s27, s27, s31
	global_load_dword v33, v74, s[24:25]
	global_load_dword v65, v74, s[26:27]
	s_add_u32 s24, s24, s30
	s_addc_u32 s25, s25, s31
	s_add_u32 s26, s26, s30
	s_addc_u32 s27, s27, s31
	global_load_dword v34, v74, s[24:25]
	global_load_dword v66, v74, s[26:27]
	s_add_u32 s24, s24, s30
	s_addc_u32 s25, s25, s31
	s_add_u32 s26, s26, s30
	s_addc_u32 s27, s27, s31
	global_load_dword v35, v74, s[24:25]
	global_load_dword v67, v74, s[26:27]
	s_add_u32 s24, s24, s30
	s_addc_u32 s25, s25, s31
	s_add_u32 s26, s26, s30
	s_addc_u32 s27, s27, s31
	global_load_dword v36, v74, s[24:25]
	global_load_dword v68, v74, s[26:27]
	s_add_u32 s24, s24, s30
	s_addc_u32 s25, s25, s31
	s_add_u32 s26, s26, s30
	s_addc_u32 s27, s27, s31
	global_load_dword v37, v74, s[24:25]
	global_load_dword v69, v74, s[26:27]
	s_add_u32 s24, s24, s30
	s_addc_u32 s25, s25, s31
	s_add_u32 s26, s26, s30
	s_addc_u32 s27, s27, s31
	global_load_dword v38, v74, s[24:25]
	global_load_dword v70, v74, s[26:27]
	s_add_u32 s24, s24, s30
	s_addc_u32 s25, s25, s31
	s_add_u32 s26, s26, s30
	s_addc_u32 s27, s27, s31
	global_load_dword v39, v74, s[24:25]
	global_load_dword v71, v74, s[26:27]
	v_mov_b32_e32 v72, 0
	v_mov_b32_e32 v73, 1.0
	s_waitcnt vmcnt(0)
; __device__ void phase_scan(const Params& p) {
;     ...
;         for (int st = 0; st < NCH; st += 64) {
;             float ab[64], hb[64];
; #pragma unroll
;             for (int i = 0; i < 64; ++i) { ab[i] = Aprod[base + (long)(st + i) * step * 512]; hb[i] = Hend[base + (long)(st + i) * step * 512]; }
; #pragma unroll
;             for (int i = 0; i < 64; ++i) { carry[base + (long)(st + i) * step * 512] = hc; hc = ab[i] * hc + hb[i]; }
	v_fma_f32 v72, v8, v72, v40
	v_mul_f32_e32 v73, v73, v8
	v_fma_f32 v72, v9, v72, v41
	v_mul_f32_e32 v73, v73, v9
	v_fma_f32 v72, v10, v72, v42
	v_mul_f32_e32 v73, v73, v10
	v_fma_f32 v72, v11, v72, v43
	v_mul_f32_e32 v73, v73, v11
	v_fma_f32 v72, v12, v72, v44
	v_mul_f32_e32 v73, v73, v12
	v_fma_f32 v72, v13, v72, v45
	v_mul_f32_e32 v73, v73, v13
	v_fma_f32 v72, v14, v72, v46
	v_mul_f32_e32 v73, v73, v14
	v_fma_f32 v72, v15, v72, v47
	v_mul_f32_e32 v73, v73, v15
	v_fma_f32 v72, v16, v72, v48
	v_mul_f32_e32 v73, v73, v16
	v_fma_f32 v72, v17, v72, v49
	v_mul_f32_e32 v73, v73, v17
	v_fma_f32 v72, v18, v72, v50
	v_mul_f32_e32 v73, v73, v18
	v_fma_f32 v72, v19, v72, v51
	v_mul_f32_e32 v73, v73, v19
	v_fma_f32 v72, v20, v72, v52
	v_mul_f32_e32 v73, v73, v20
	v_fma_f32 v72, v21, v72, v53
	v_mul_f32_e32 v73, v73, v21
	v_fma_f32 v72, v22, v72, v54
	v_mul_f32_e32 v73, v73, v22
	v_fma_f32 v72, v23, v72, v55
	v_mul_f32_e32 v73, v73, v23
	v_fma_f32 v72, v24, v72, v56
	v_mul_f32_e32 v73, v73, v24
	v_fma_f32 v72, v25, v72, v57
	v_mul_f32_e32 v73, v73, v25
	v_fma_f32 v72, v26, v72, v58
	v_mul_f32_e32 v73, v73, v26
	v_fma_f32 v72, v27, v72, v59
	v_mul_f32_e32 v73, v73, v27
	v_fma_f32 v72, v28, v72, v60
	v_mul_f32_e32 v73, v73, v28
	v_fma_f32 v72, v29, v72, v61
	v_mul_f32_e32 v73, v73, v29
	v_fma_f32 v72, v30, v72, v62
	v_mul_f32_e32 v73, v73, v30
	v_fma_f32 v72, v31, v72, v63
	v_mul_f32_e32 v73, v73, v31
	v_fma_f32 v72, v32, v72, v64
	v_mul_f32_e32 v73, v73, v32
	v_fma_f32 v72, v33, v72, v65
	v_mul_f32_e32 v73, v73, v33
	v_fma_f32 v72, v34, v72, v66
	v_mul_f32_e32 v73, v73, v34
	v_fma_f32 v72, v35, v72, v67
	v_mul_f32_e32 v73, v73, v35
	v_fma_f32 v72, v36, v72, v68
	v_mul_f32_e32 v73, v73, v36
	v_fma_f32 v72, v37, v72, v69
	v_mul_f32_e32 v73, v73, v37
	v_fma_f32 v72, v38, v72, v70
	v_mul_f32_e32 v73, v73, v38
	v_fma_f32 v72, v39, v72, v71
	v_mul_f32_e32 v73, v73, v39
	v_add_u32_e32 v78, 56, v0
	v_and_b32_e32 v78, 63, v78
	v_lshlrev_b32_e32 v78, 2, v78
	ds_bpermute_b32 v79, v78, v72
	ds_bpermute_b32 v80, v78, v73
	v_cmp_lt_u32_e32 vcc, 7, v0
	s_waitcnt lgkmcnt(0)
	v_fma_f32 v81, v73, v79, v72
	v_mul_f32_e32 v82, v73, v80
	s_nop 0
	v_cndmask_b32_e32 v72, v72, v81, vcc
	v_cndmask_b32_e32 v73, v73, v82, vcc
	s_nop 0
	v_add_u32_e32 v78, 48, v0
	v_and_b32_e32 v78, 63, v78
	v_lshlrev_b32_e32 v78, 2, v78
	ds_bpermute_b32 v79, v78, v72
	ds_bpermute_b32 v80, v78, v73
	v_cmp_lt_u32_e32 vcc, 15, v0
	s_waitcnt lgkmcnt(0)
	v_fma_f32 v81, v73, v79, v72
	v_mul_f32_e32 v82, v73, v80
	s_nop 0
	v_cndmask_b32_e32 v72, v72, v81, vcc
	v_cndmask_b32_e32 v73, v73, v82, vcc
	s_nop 0
	v_add_u32_e32 v78, 32, v0
	v_and_b32_e32 v78, 63, v78
	v_lshlrev_b32_e32 v78, 2, v78
	ds_bpermute_b32 v79, v78, v72
	ds_bpermute_b32 v80, v78, v73
	v_cmp_lt_u32_e32 vcc, 31, v0
	s_waitcnt lgkmcnt(0)
	v_fma_f32 v81, v73, v79, v72
	v_mul_f32_e32 v82, v73, v80
	s_nop 0
	v_cndmask_b32_e32 v72, v72, v81, vcc
	v_cndmask_b32_e32 v73, v73, v82, vcc
	s_nop 0
	v_add_u32_e32 v78, 56, v0
	v_and_b32_e32 v78, 63, v78
	v_lshlrev_b32_e32 v78, 2, v78
	ds_bpermute_b32 v79, v78, v72
	v_cmp_lt_u32_e32 vcc, 7, v0
	s_nop 1
	s_waitcnt lgkmcnt(0)
	v_cndmask_b32_e32 v72, 0, v79, vcc
	v_mov_b32_e32 v83, v72
	global_store_dword v74, v83, s[28:29]
	v_fma_f32 v72, v8, v72, v40
	s_add_u32 s28, s28, s30
	s_addc_u32 s29, s29, s31
	v_mov_b32_e32 v84, v72
	global_store_dword v74, v84, s[28:29]
	v_fma_f32 v72, v9, v72, v41
	s_add_u32 s28, s28, s30
	s_addc_u32 s29, s29, s31
	v_mov_b32_e32 v83, v72
	global_store_dword v74, v83, s[28:29]
	v_fma_f32 v72, v10, v72, v42
	s_add_u32 s28, s28, s30
	s_addc_u32 s29, s29, s31
	v_mov_b32_e32 v84, v72
	global_store_dword v74, v84, s[28:29]
	v_fma_f32 v72, v11, v72, v43
	s_add_u32 s28, s28, s30
	s_addc_u32 s29, s29, s31
	v_mov_b32_e32 v83, v72
	global_store_dword v74, v83, s[28:29]
	v_fma_f32 v72, v12, v72, v44
	s_add_u32 s28, s28, s30
	s_addc_u32 s29, s29, s31
	v_mov_b32_e32 v84, v72
	global_store_dword v74, v84, s[28:29]
	v_fma_f32 v72, v13, v72, v45
	s_add_u32 s28, s28, s30
	s_addc_u32 s29, s29, s31
	v_mov_b32_e32 v83, v72
	global_store_dword v74, v83, s[28:29]
	v_fma_f32 v72, v14, v72, v46
	s_add_u32 s28, s28, s30
	s_addc_u32 s29, s29, s31
	v_mov_b32_e32 v84, v72
	global_store_dword v74, v84, s[28:29]
	v_fma_f32 v72, v15, v72, v47
	s_add_u32 s28, s28, s30
	s_addc_u32 s29, s29, s31
	v_mov_b32_e32 v83, v72
	global_store_dword v74, v83, s[28:29]
	v_fma_f32 v72, v16, v72, v48
	s_add_u32 s28, s28, s30
	s_addc_u32 s29, s29, s31
	v_mov_b32_e32 v84, v72
	global_store_dword v74, v84, s[28:29]
	v_fma_f32 v72, v17, v72, v49
	s_add_u32 s28, s28, s30
	s_addc_u32 s29, s29, s31
	v_mov_b32_e32 v83, v72
	global_store_dword v74, v83, s[28:29]
	v_fma_f32 v72, v18, v72, v50
	s_add_u32 s28, s28, s30
	s_addc_u32 s29, s29, s31
	v_mov_b32_e32 v84, v72
	global_store_dword v74, v84, s[28:29]
	v_fma_f32 v72, v19, v72, v51
	s_add_u32 s28, s28, s30
	s_addc_u32 s29, s29, s31
	v_mov_b32_e32 v83, v72
	global_store_dword v74, v83, s[28:29]
	v_fma_f32 v72, v20, v72, v52
	s_add_u32 s28, s28, s30
	s_addc_u32 s29, s29, s31
	v_mov_b32_e32 v84, v72
	global_store_dword v74, v84, s[28:29]
	v_fma_f32 v72, v21, v72, v53
	s_add_u32 s28, s28, s30
	s_addc_u32 s29, s29, s31
	v_mov_b32_e32 v83, v72
	global_store_dword v74, v83, s[28:29]
	v_fma_f32 v72, v22, v72, v54
	s_add_u32 s28, s28, s30
	s_addc_u32 s29, s29, s31
	v_mov_b32_e32 v84, v72
	global_store_dword v74, v84, s[28:29]
	v_fma_f32 v72, v23, v72, v55
	s_add_u32 s28, s28, s30
	s_addc_u32 s29, s29, s31
	v_mov_b32_e32 v83, v72
	global_store_dword v74, v83, s[28:29]
	v_fma_f32 v72, v24, v72, v56
	s_add_u32 s28, s28, s30
	s_addc_u32 s29, s29, s31
	v_mov_b32_e32 v84, v72
; __device__ void phase_scan(const Params& p) {
;     ...
;             for (int st = 0; st < NCH; st += 64) {
;                 bf16_t ub[64]; float db[64];
; #pragma unroll
;                 for (int i = 0; i < 64; ++i) { ub[i] = up[(long)(st + i) * step * 32768]; db[i] = dp[(long)(st + i) * step * 256]; }
;     ...
;             for (int i = 0; i < 64; ++i) { ab[i] = Aprod[base + (long)(st + i) * step * 512]; hb[i] = Hend[base + (long)(st + i) * step * 512]; }
; #pragma unroll
;             for (int i = 0; i < 64; ++i) { carry[base + (long)(st + i) * step * 512] = hc; hc = ab[i] * hc + hb[i]; }
	global_store_dword v74, v84, s[28:29]
	v_fma_f32 v72, v25, v72, v57
	s_add_u32 s28, s28, s30
	s_addc_u32 s29, s29, s31
	v_mov_b32_e32 v83, v72
	global_store_dword v74, v83, s[28:29]
	v_fma_f32 v72, v26, v72, v58
	s_add_u32 s28, s28, s30
	s_addc_u32 s29, s29, s31
	v_mov_b32_e32 v84, v72
	global_store_dword v74, v84, s[28:29]
	v_fma_f32 v72, v27, v72, v59
	s_add_u32 s28, s28, s30
	s_addc_u32 s29, s29, s31
	v_mov_b32_e32 v83, v72
	global_store_dword v74, v83, s[28:29]
	v_fma_f32 v72, v28, v72, v60
	s_add_u32 s28, s28, s30
	s_addc_u32 s29, s29, s31
	v_mov_b32_e32 v84, v72
	global_store_dword v74, v84, s[28:29]
	v_fma_f32 v72, v29, v72, v61
	s_add_u32 s28, s28, s30
	s_addc_u32 s29, s29, s31
	v_mov_b32_e32 v83, v72
	global_store_dword v74, v83, s[28:29]
	v_fma_f32 v72, v30, v72, v62
	s_add_u32 s28, s28, s30
	s_addc_u32 s29, s29, s31
	v_mov_b32_e32 v84, v72
	global_store_dword v74, v84, s[28:29]
	v_fma_f32 v72, v31, v72, v63
	s_add_u32 s28, s28, s30
	s_addc_u32 s29, s29, s31
	v_mov_b32_e32 v83, v72
	global_store_dword v74, v83, s[28:29]
	v_fma_f32 v72, v32, v72, v64
	s_add_u32 s28, s28, s30
	s_addc_u32 s29, s29, s31
	v_mov_b32_e32 v84, v72
	global_store_dword v74, v84, s[28:29]
	v_fma_f32 v72, v33, v72, v65
	s_add_u32 s28, s28, s30
	s_addc_u32 s29, s29, s31
	v_mov_b32_e32 v83, v72
	global_store_dword v74, v83, s[28:29]
	v_fma_f32 v72, v34, v72, v66
	s_add_u32 s28, s28, s30
	s_addc_u32 s29, s29, s31
	v_mov_b32_e32 v84, v72
	global_store_dword v74, v84, s[28:29]
	v_fma_f32 v72, v35, v72, v67
	s_add_u32 s28, s28, s30
	s_addc_u32 s29, s29, s31
	v_mov_b32_e32 v83, v72
	global_store_dword v74, v83, s[28:29]
	v_fma_f32 v72, v36, v72, v68
	s_add_u32 s28, s28, s30
	s_addc_u32 s29, s29, s31
	v_mov_b32_e32 v84, v72
	global_store_dword v74, v84, s[28:29]
	v_fma_f32 v72, v37, v72, v69
	s_add_u32 s28, s28, s30
	s_addc_u32 s29, s29, s31
	v_mov_b32_e32 v83, v72
	global_store_dword v74, v83, s[28:29]
	v_fma_f32 v72, v38, v72, v70
	s_add_u32 s28, s28, s30
	s_addc_u32 s29, s29, s31
	v_mov_b32_e32 v84, v72
	global_store_dword v74, v84, s[28:29]
	v_fma_f32 v72, v39, v72, v71
	global_load_ushort v8, v1, s[16:17] nt
	s_add_u32 s16, s16, s20
	s_addc_u32 s17, s17, s21
	global_load_ushort v9, v1, s[16:17] nt
	s_add_u32 s16, s16, s20
	s_addc_u32 s17, s17, s21
	global_load_ushort v10, v1, s[16:17] nt
	s_add_u32 s16, s16, s20
	s_addc_u32 s17, s17, s21
	global_load_ushort v11, v1, s[16:17] nt
	s_add_u32 s16, s16, s20
	s_addc_u32 s17, s17, s21
	global_load_ushort v12, v1, s[16:17] nt
	s_add_u32 s16, s16, s20
	s_addc_u32 s17, s17, s21
	global_load_ushort v13, v1, s[16:17] nt
	s_add_u32 s16, s16, s20
	s_addc_u32 s17, s17, s21
	global_load_ushort v14, v1, s[16:17] nt
	s_add_u32 s16, s16, s20
	s_addc_u32 s17, s17, s21
	global_load_ushort v15, v1, s[16:17] nt
	s_add_u32 s16, s16, s20
	s_addc_u32 s17, s17, s21
	global_load_ushort v16, v1, s[16:17] nt
	s_add_u32 s16, s16, s20
	s_addc_u32 s17, s17, s21
	global_load_ushort v17, v1, s[16:17] nt
	s_add_u32 s16, s16, s20
	s_addc_u32 s17, s17, s21
	global_load_ushort v18, v1, s[16:17] nt
	s_add_u32 s16, s16, s20
	s_addc_u32 s17, s17, s21
	global_load_ushort v19, v1, s[16:17] nt
	s_add_u32 s16, s16, s20
	s_addc_u32 s17, s17, s21
	global_load_ushort v20, v1, s[16:17] nt
	s_add_u32 s16, s16, s20
	s_addc_u32 s17, s17, s21
	global_load_ushort v21, v1, s[16:17] nt
	s_add_u32 s16, s16, s20
	s_addc_u32 s17, s17, s21
	global_load_ushort v22, v1, s[16:17] nt
	s_add_u32 s16, s16, s20
	s_addc_u32 s17, s17, s21
	global_load_ushort v23, v1, s[16:17] nt
	s_add_u32 s16, s16, s20
	s_addc_u32 s17, s17, s21
	global_load_ushort v24, v1, s[16:17] nt
	s_add_u32 s16, s16, s20
	s_addc_u32 s17, s17, s21
	global_load_ushort v25, v1, s[16:17] nt
	s_add_u32 s16, s16, s20
	s_addc_u32 s17, s17, s21
	global_load_ushort v26, v1, s[16:17] nt
	s_add_u32 s16, s16, s20
	s_addc_u32 s17, s17, s21
	global_load_ushort v27, v1, s[16:17] nt
	s_add_u32 s16, s16, s20
	s_addc_u32 s17, s17, s21
	global_load_ushort v28, v1, s[16:17] nt
	s_add_u32 s16, s16, s20
	s_addc_u32 s17, s17, s21
	global_load_ushort v29, v1, s[16:17] nt
	s_add_u32 s16, s16, s20
	s_addc_u32 s17, s17, s21
	global_load_ushort v30, v1, s[16:17] nt
	s_add_u32 s16, s16, s20
	s_addc_u32 s17, s17, s21
	global_load_ushort v31, v1, s[16:17] nt
	s_add_u32 s16, s16, s20
	s_addc_u32 s17, s17, s21
	global_load_ushort v32, v1, s[16:17] nt
	s_add_u32 s16, s16, s20
	s_addc_u32 s17, s17, s21
	global_load_ushort v33, v1, s[16:17] nt
	s_add_u32 s16, s16, s20
	s_addc_u32 s17, s17, s21
	global_load_ushort v34, v1, s[16:17] nt
	s_add_u32 s16, s16, s20
	s_addc_u32 s17, s17, s21
	global_load_ushort v35, v1, s[16:17] nt
	s_add_u32 s16, s16, s20
	s_addc_u32 s17, s17, s21
	global_load_ushort v36, v1, s[16:17] nt
	s_add_u32 s16, s16, s20
	s_addc_u32 s17, s17, s21
	global_load_ushort v37, v1, s[16:17] nt
	s_add_u32 s16, s16, s20
	s_addc_u32 s17, s17, s21
	global_load_ushort v38, v1, s[16:17] nt
	s_add_u32 s16, s16, s20
	s_addc_u32 s17, s17, s21
	global_load_ushort v39, v1, s[16:17] nt
	s_add_u32 s16, s16, s20
	s_addc_u32 s17, s17, s21
	global_load_ushort v40, v1, s[16:17] nt
	s_add_u32 s16, s16, s20
	s_addc_u32 s17, s17, s21
	global_load_ushort v41, v1, s[16:17] nt
	s_add_u32 s16, s16, s20
	s_addc_u32 s17, s17, s21
	global_load_ushort v42, v1, s[16:17] nt
	s_add_u32 s16, s16, s20
	s_addc_u32 s17, s17, s21
	global_load_ushort v43, v1, s[16:17] nt
	s_add_u32 s16, s16, s20
	s_addc_u32 s17, s17, s21
	global_load_ushort v44, v1, s[16:17] nt
	s_add_u32 s16, s16, s20
	s_addc_u32 s17, s17, s21
	global_load_ushort v45, v1, s[16:17] nt
	s_add_u32 s16, s16, s20
	s_addc_u32 s17, s17, s21
	global_load_ushort v46, v1, s[16:17] nt
	s_add_u32 s16, s16, s20
; __device__ void phase_scan(const Params& p) {
;     ...
;             for (int st = 0; st < NCH; st += 64) {
;                 bf16_t ub[64]; float db[64];
; #pragma unroll
;                 for (int i = 0; i < 64; ++i) { ub[i] = up[(long)(st + i) * step * 32768]; db[i] = dp[(long)(st + i) * step * 256]; }
	s_addc_u32 s17, s17, s21
	global_load_ushort v47, v1, s[16:17] nt
	s_add_u32 s16, s16, s20
	s_addc_u32 s17, s17, s21
	global_load_ushort v48, v1, s[16:17] nt
	s_add_u32 s16, s16, s20
	s_addc_u32 s17, s17, s21
	global_load_ushort v49, v1, s[16:17] nt
	s_add_u32 s16, s16, s20
	s_addc_u32 s17, s17, s21
	global_load_ushort v50, v1, s[16:17] nt
	s_add_u32 s16, s16, s20
	s_addc_u32 s17, s17, s21
	global_load_ushort v51, v1, s[16:17] nt
	s_add_u32 s16, s16, s20
	s_addc_u32 s17, s17, s21
	global_load_ushort v52, v1, s[16:17] nt
	s_add_u32 s16, s16, s20
	s_addc_u32 s17, s17, s21
	global_load_ushort v53, v1, s[16:17] nt
	s_add_u32 s16, s16, s20
	s_addc_u32 s17, s17, s21
	global_load_ushort v54, v1, s[16:17] nt
	s_add_u32 s16, s16, s20
	s_addc_u32 s17, s17, s21
	global_load_ushort v55, v1, s[16:17] nt
	s_add_u32 s16, s16, s20
	s_addc_u32 s17, s17, s21
	global_load_ushort v56, v1, s[16:17] nt
	s_add_u32 s16, s16, s20
	s_addc_u32 s17, s17, s21
	global_load_ushort v57, v1, s[16:17] nt
	s_add_u32 s16, s16, s20
	s_addc_u32 s17, s17, s21
	global_load_ushort v58, v1, s[16:17] nt
	s_add_u32 s16, s16, s20
	s_addc_u32 s17, s17, s21
	global_load_ushort v59, v1, s[16:17] nt
	s_add_u32 s16, s16, s20
	s_addc_u32 s17, s17, s21
	global_load_ushort v60, v1, s[16:17] nt
	s_add_u32 s16, s16, s20
	s_addc_u32 s17, s17, s21
	global_load_ushort v61, v1, s[16:17] nt
	s_add_u32 s16, s16, s20
	s_addc_u32 s17, s17, s21
	global_load_ushort v62, v1, s[16:17] nt
	s_add_u32 s16, s16, s20
	s_addc_u32 s17, s17, s21
	global_load_ushort v63, v1, s[16:17] nt
	s_add_u32 s16, s16, s20
	s_addc_u32 s17, s17, s21
	global_load_ushort v64, v1, s[16:17] nt
	s_add_u32 s16, s16, s20
	s_addc_u32 s17, s17, s21
	global_load_ushort v65, v1, s[16:17] nt
	s_add_u32 s16, s16, s20
	s_addc_u32 s17, s17, s21
	global_load_ushort v66, v1, s[16:17] nt
	s_add_u32 s16, s16, s20
	s_addc_u32 s17, s17, s21
	global_load_ushort v67, v1, s[16:17] nt
	s_add_u32 s16, s16, s20
	s_addc_u32 s17, s17, s21
	global_load_ushort v68, v1, s[16:17] nt
	s_add_u32 s16, s16, s20
	s_addc_u32 s17, s17, s21
	global_load_ushort v69, v1, s[16:17] nt
	s_add_u32 s16, s16, s20
	s_addc_u32 s17, s17, s21
	global_load_ushort v70, v1, s[16:17] nt
	s_add_u32 s16, s16, s20
	s_addc_u32 s17, s17, s21
	global_load_ushort v71, v1, s[16:17] nt
	s_add_u32 s16, s16, s20
	s_addc_u32 s17, s17, s21
	global_load_ushort v72, v1, s[16:17] nt
	s_add_u32 s16, s16, s20
	s_addc_u32 s17, s17, s21
	global_load_ushort v73, v1, s[16:17] nt
	s_add_u32 s16, s16, s20
	s_addc_u32 s17, s17, s21
	global_load_ushort v74, v1, s[16:17] nt
	s_add_u32 s16, s16, s20
	s_addc_u32 s17, s17, s21
	global_load_ushort v75, v1, s[16:17] nt
	s_add_u32 s16, s16, s20
	s_addc_u32 s17, s17, s21
	global_load_ushort v76, v1, s[16:17] nt
	s_add_u32 s16, s16, s20
	s_addc_u32 s17, s17, s21
	global_load_ushort v77, v1, s[16:17] nt
	s_add_u32 s16, s16, s20
	s_addc_u32 s17, s17, s21
	global_load_ushort v78, v1, s[16:17] nt
	s_add_u32 s16, s16, s20
	s_addc_u32 s17, s17, s21
	global_load_ushort v79, v1, s[16:17] nt
	s_add_u32 s16, s16, s20
	s_addc_u32 s17, s17, s21
	global_load_ushort v80, v1, s[16:17] nt
	s_add_u32 s16, s16, s20
	s_addc_u32 s17, s17, s21
	global_load_ushort v81, v1, s[16:17] nt
	s_add_u32 s16, s16, s20
	s_addc_u32 s17, s17, s21
	global_load_ushort v82, v1, s[16:17] nt
	s_add_u32 s16, s16, s20
	s_addc_u32 s17, s17, s21
	global_load_ushort v83, v1, s[16:17] nt
	s_add_u32 s16, s16, s20
	s_addc_u32 s17, s17, s21
	global_load_ushort v84, v1, s[16:17] nt
	s_add_u32 s16, s16, s20
	s_addc_u32 s17, s17, s21
	global_load_ushort v85, v1, s[16:17] nt
	s_add_u32 s16, s16, s20
	s_addc_u32 s17, s17, s21
	global_load_ushort v86, v1, s[16:17] nt
	s_add_u32 s16, s16, s20
	s_addc_u32 s17, s17, s21
	global_load_ushort v87, v1, s[16:17] nt
	s_add_u32 s16, s16, s20
	s_addc_u32 s17, s17, s21
	global_load_ushort v88, v1, s[16:17] nt
	s_add_u32 s16, s16, s20
	s_addc_u32 s17, s17, s21
	global_load_ushort v89, v1, s[16:17] nt
	s_add_u32 s16, s16, s20
	s_addc_u32 s17, s17, s21
	global_load_ushort v90, v1, s[16:17] nt
	s_add_u32 s16, s16, s20
	s_addc_u32 s17, s17, s21
	global_load_ushort v91, v1, s[16:17] nt
; __device__ void phase_scan(const Params& p) {
;     ...
;             for (int st = 0; st < NCH; st += 64) {
;                 bf16_t ub[64]; float db[64];
; #pragma unroll
;                 for (int i = 0; i < 64; ++i) { ub[i] = up[(long)(st + i) * step * 32768]; db[i] = dp[(long)(st + i) * step * 256]; }
	s_add_u32 s16, s16, s20
	s_addc_u32 s17, s17, s21
	global_load_ushort v92, v1, s[16:17] nt
	s_add_u32 s16, s16, s20
	s_addc_u32 s17, s17, s21
	global_load_ushort v93, v1, s[16:17] nt
	s_add_u32 s16, s16, s20
	s_addc_u32 s17, s17, s21
	global_load_ushort v94, v1, s[16:17] nt
	s_add_u32 s16, s16, s20
	s_addc_u32 s17, s17, s21
	global_load_ushort v95, v1, s[16:17] nt
	s_add_u32 s16, s16, s20
	s_addc_u32 s17, s17, s21
	global_load_ushort v96, v1, s[16:17] nt
	s_add_u32 s16, s16, s20
	s_addc_u32 s17, s17, s21
	global_load_ushort v97, v1, s[16:17] nt
	s_add_u32 s16, s16, s20
	s_addc_u32 s17, s17, s21
	global_load_ushort v98, v1, s[16:17] nt
	s_add_u32 s16, s16, s20
	s_addc_u32 s17, s17, s21
	global_load_ushort v99, v1, s[16:17] nt
	s_add_u32 s16, s16, s20
	s_addc_u32 s17, s17, s21
	global_load_ushort v100, v1, s[16:17] nt
	s_add_u32 s16, s16, s20
	s_addc_u32 s17, s17, s21
	global_load_ushort v101, v1, s[16:17] nt
	s_add_u32 s16, s16, s20
	s_addc_u32 s17, s17, s21
	global_load_ushort v102, v1, s[16:17] nt
	s_add_u32 s16, s16, s20
	s_addc_u32 s17, s17, s21
	global_load_ushort v103, v1, s[16:17] nt
	s_add_u32 s16, s16, s20
	s_addc_u32 s17, s17, s21
	global_load_ushort v104, v1, s[16:17] nt
	s_add_u32 s16, s16, s20
	s_addc_u32 s17, s17, s21
	global_load_ushort v105, v1, s[16:17] nt
	s_add_u32 s16, s16, s20
	s_addc_u32 s17, s17, s21
	global_load_ushort v106, v1, s[16:17] nt
	s_add_u32 s16, s16, s20
	s_addc_u32 s17, s17, s21
	global_load_ushort v107, v1, s[16:17] nt
	s_add_u32 s16, s16, s20
	s_addc_u32 s17, s17, s21
	global_load_ushort v108, v1, s[16:17] nt
	s_add_u32 s16, s16, s20
	s_addc_u32 s17, s17, s21
	global_load_ushort v109, v1, s[16:17] nt
	s_add_u32 s16, s16, s20
	s_addc_u32 s17, s17, s21
	global_load_ushort v110, v1, s[16:17] nt
	s_add_u32 s16, s16, s20
	s_addc_u32 s17, s17, s21
	global_load_ushort v111, v1, s[16:17] nt
	s_add_u32 s16, s16, s20
	s_addc_u32 s17, s17, s21
	global_load_ushort v112, v1, s[16:17] nt
	s_add_u32 s16, s16, s20
	s_addc_u32 s17, s17, s21
	global_load_ushort v113, v1, s[16:17] nt
	s_add_u32 s16, s16, s20
	s_addc_u32 s17, s17, s21
	global_load_ushort v114, v1, s[16:17] nt
	s_add_u32 s16, s16, s20
	s_addc_u32 s17, s17, s21
	global_load_ushort v115, v1, s[16:17] nt
	s_add_u32 s16, s16, s20
	s_addc_u32 s17, s17, s21
	global_load_ushort v116, v1, s[16:17] nt
	s_add_u32 s16, s16, s20
	s_addc_u32 s17, s17, s21
	global_load_ushort v117, v1, s[16:17] nt
	s_add_u32 s16, s16, s20
	s_addc_u32 s17, s17, s21
	global_load_ushort v118, v1, s[16:17] nt
	s_add_u32 s16, s16, s20
	s_addc_u32 s17, s17, s21
	global_load_ushort v119, v1, s[16:17] nt
	s_add_u32 s16, s16, s20
	s_addc_u32 s17, s17, s21
	global_load_ushort v120, v1, s[16:17] nt
	s_add_u32 s16, s16, s20
	s_addc_u32 s17, s17, s21
	global_load_ushort v121, v1, s[16:17] nt
	s_add_u32 s16, s16, s20
	s_addc_u32 s17, s17, s21
	global_load_ushort v122, v1, s[16:17] nt
	s_add_u32 s16, s16, s20
	s_addc_u32 s17, s17, s21
	global_load_ushort v123, v1, s[16:17] nt
	s_add_u32 s16, s16, s20
	s_addc_u32 s17, s17, s21
	global_load_ushort v124, v1, s[16:17] nt
	s_add_u32 s16, s16, s20
	s_addc_u32 s17, s17, s21
	global_load_ushort v125, v1, s[16:17] nt
	s_add_u32 s16, s16, s20
	s_addc_u32 s17, s17, s21
	global_load_ushort v126, v1, s[16:17] nt
	s_add_u32 s16, s16, s20
	s_addc_u32 s17, s17, s21
	global_load_ushort v127, v1, s[16:17] nt
	s_add_u32 s16, s16, s20
	s_addc_u32 s17, s17, s21
	global_load_ushort v128, v1, s[16:17] nt
	s_add_u32 s16, s16, s20
	s_addc_u32 s17, s17, s21
	global_load_ushort v129, v1, s[16:17] nt
	s_add_u32 s16, s16, s20
	s_addc_u32 s17, s17, s21
	global_load_ushort v130, v1, s[16:17] nt
	s_add_u32 s16, s16, s20
	s_addc_u32 s17, s17, s21
	global_load_ushort v131, v1, s[16:17] nt
	s_add_u32 s16, s16, s20
	s_addc_u32 s17, s17, s21
	global_load_ushort v132, v1, s[16:17] nt
	s_add_u32 s16, s16, s20
	s_addc_u32 s17, s17, s21
	global_load_ushort v133, v1, s[16:17] nt
	s_add_u32 s16, s16, s20
	s_addc_u32 s17, s17, s21
	global_load_ushort v134, v1, s[16:17] nt
	s_add_u32 s16, s16, s20
	s_addc_u32 s17, s17, s21
	global_load_ushort v135, v1, s[16:17] nt
